# plus NSA QK fragment reads pipelined (7 buffers, counted lgkmcnt)
# baseline (speedup 1.0000x reference)
.LBB0_740:
	v_mov_b32_e32 v1, s74
	ds_read_b32 v1, v1
	s_and_b32 s68, s69, 1
	s_mul_i32 s69, s68, 0x2400
	s_add_i32 s91, s69, 0
	s_lshl_b32 s68, s68, 9
	s_waitcnt lgkmcnt(0)
	v_readfirstlane_b32 s69, v1
	s_and_b32 s90, s69, 0xff
	v_lshl_add_u32 v2, s90, 6, v155
	v_cvt_f32_i32_e32 v2, v2
	v_and_b32_e32 v1, 0x100, v1
	v_cmp_eq_u32_e32 vcc, 0, v1
	s_sub_i32 s88, s91, s68
	v_mul_f32_e32 v1, v149, v2
	s_and_b64 vcc, exec, vcc
	s_mov_b64 s[68:69], -1
	s_cbranch_vccnz .LBB0_844
	v_add3_u32 v14, s91, v148, v107
	v_add3_u32 v15, s91, v157, v107
	ds_read_b128 v[2:5], v14
	ds_read_b128 v[6:9], v14 offset:32
	ds_read_b128 v[10:13], v14 offset:64
	ds_read_b128 v[166:169], v14 offset:96
	ds_read_b128 v[170:173], v15
	ds_read_b128 v[174:177], v15 offset:32
	ds_read_b128 v[178:181], v15 offset:64
	s_cmp_eq_u32 s90, s75
	s_cselect_b32 s68, 2, 0
	s_cmp_lg_u32 s90, s78
	s_cselect_b32 s76, s68, 1
	s_cmp_gt_i32 s76, 1
	s_mov_b64 s[68:69], -1
	s_waitcnt lgkmcnt(6)
	v_mfma_f32_32x32x16_bf16 v[48:63], v[2:5], v[88:91], 0
	ds_read_b128 v[2:5], v15 offset:96
	s_waitcnt lgkmcnt(6)
	v_mfma_f32_32x32x16_bf16 v[48:63], v[6:9], v[80:83], v[48:63]
	s_waitcnt lgkmcnt(5)
	v_mfma_f32_32x32x16_bf16 v[48:63], v[10:13], v[84:87], v[48:63]
	s_waitcnt lgkmcnt(4)
	v_mfma_f32_32x32x16_bf16 v[48:63], v[166:169], v[92:95], v[48:63]
	s_waitcnt lgkmcnt(3)
	v_mfma_f32_32x32x16_bf16 v[64:79], v[170:173], v[88:91], 0
	s_waitcnt lgkmcnt(2)
	v_mfma_f32_32x32x16_bf16 v[64:79], v[174:177], v[80:83], v[64:79]
	s_waitcnt lgkmcnt(1)
	v_mfma_f32_32x32x16_bf16 v[64:79], v[178:181], v[84:87], v[64:79]
	s_waitcnt lgkmcnt(0)
	v_mfma_f32_32x32x16_bf16 v[64:79], v[2:5], v[92:95], v[64:79]
	v_add_f32_e32 v2, 0, v1
	v_fmamk_f32 v5, v149, 0x42000000, v1
	v_fmac_f32_e32 v2, 0x3e38aa3b, v48
	s_nop 8
	v_fmac_f32_e32 v5, 0x3e38aa3b, v64
	s_cbranch_scc0 .LBB0_743
	v_readlane_b32 s4, v254, 15
	v_readlane_b32 s5, v254, 16
	v_cndmask_b32_e64 v3, v194, v5, s[86:87]
	s_mov_b64 s[68:69], 0
	v_cndmask_b32_e64 v4, v194, v2, s[4:5]

.LBB0_844:
	s_and_b64 vcc, exec, s[68:69]
	s_cbranch_vccz .LBB0_840
	v_lshrrev_b32_e32 v2, s90, v152
	v_and_b32_e32 v2, 1, v2
	v_cmp_eq_u32_e64 s[68:69], 1, v2
	v_bfe_u32 v2, v152, s90, 1
	v_cmp_ne_u32_e32 vcc, 0, v2
	s_cbranch_vccz .LBB0_849
	v_add3_u32 v14, s91, v148, v107
	v_add3_u32 v15, s91, v157, v107
	ds_read_b128 v[2:5], v14
	ds_read_b128 v[6:9], v14 offset:32
	ds_read_b128 v[10:13], v14 offset:64
	ds_read_b128 v[166:169], v14 offset:96
	ds_read_b128 v[170:173], v15
	ds_read_b128 v[174:177], v15 offset:32
	ds_read_b128 v[178:181], v15 offset:64
	s_cmp_eq_u32 s90, s78
	v_readlane_b32 s4, v254, 15
	v_readlane_b32 s5, v254, 16
	s_waitcnt lgkmcnt(6)
	v_mfma_f32_32x32x16_bf16 v[48:63], v[2:5], v[88:91], 0
	ds_read_b128 v[2:5], v15 offset:96
	s_waitcnt lgkmcnt(6)
	v_mfma_f32_32x32x16_bf16 v[48:63], v[6:9], v[80:83], v[48:63]
	s_waitcnt lgkmcnt(5)
	v_mfma_f32_32x32x16_bf16 v[48:63], v[10:13], v[84:87], v[48:63]
	s_waitcnt lgkmcnt(4)
	v_mfma_f32_32x32x16_bf16 v[48:63], v[166:169], v[92:95], v[48:63]
	s_waitcnt lgkmcnt(3)
	v_mfma_f32_32x32x16_bf16 v[64:79], v[170:173], v[88:91], 0
	s_waitcnt lgkmcnt(2)
	v_mfma_f32_32x32x16_bf16 v[64:79], v[174:177], v[80:83], v[64:79]
	s_waitcnt lgkmcnt(1)
	v_mfma_f32_32x32x16_bf16 v[64:79], v[178:181], v[84:87], v[64:79]
	s_cselect_b64 s[90:91], -1, 0
	s_and_b64 vcc, s[90:91], s[4:5]
	s_mov_b32 s4, 0xff800000
	s_waitcnt lgkmcnt(0)
	v_mfma_f32_32x32x16_bf16 v[64:79], v[2:5], v[92:95], v[64:79]
	v_fmamk_f32 v7, v149, 0x42000000, v1
	v_add_f32_e32 v6, 0, v1
	s_nop 0
	v_fmac_f32_e32 v6, 0x3e38aa3b, v48
	v_cndmask_b32_e32 v2, v6, v194, vcc
	s_and_b64 vcc, s[90:91], s[86:87]
	v_fmamk_f32 v4, v149, 0x42040000, v1
	v_fmamk_f32 v5, v149, 0x420c0000, v1
	s_nop 7
	v_fmac_f32_e32 v7, 0x3e38aa3b, v64
	v_cndmask_b32_e32 v3, v7, v194, vcc
	v_cndmask_b32_e64 v6, v194, v3, s[68:69]
	v_add_f32_e32 v3, v149, v1
	v_fmac_f32_e32 v3, 0x3e38aa3b, v49
	s_and_b64 vcc, s[90:91], s[94:95]
	v_fmac_f32_e32 v4, 0x3e38aa3b, v65
	v_cndmask_b32_e32 v3, v3, v194, vcc
	s_and_b64 vcc, s[90:91], s[82:83]
	v_cndmask_b32_e32 v4, v4, v194, vcc
	v_cndmask_b32_e64 v7, v194, v2, s[68:69]
	v_cndmask_b32_e64 v9, v194, v3, s[68:69]
	v_cndmask_b32_e64 v8, v194, v4, s[68:69]
	v_max_f32_e32 v2, v7, v6
	v_max_f32_e32 v3, v9, v8
	v_max3_f32 v2, v2, s4, v3
	v_fma_f32 v3, 2.0, v149, v1
	v_fmac_f32_e32 v3, 0x3e38aa3b, v50
	v_fmamk_f32 v4, v149, 0x42080000, v1
	s_and_b64 vcc, s[90:91], s[92:93]
	v_fmac_f32_e32 v4, 0x3e38aa3b, v66
	v_cndmask_b32_e32 v3, v3, v194, vcc
	s_and_b64 vcc, s[90:91], s[96:97]
	v_cndmask_b32_e32 v4, v4, v194, vcc
	v_cndmask_b32_e64 v10, v194, v4, s[68:69]
	v_fmamk_f32 v4, v149, 0x40400000, v1
	v_readlane_b32 s4, v254, 17
	v_fmac_f32_e32 v4, 0x3e38aa3b, v51
	s_and_b64 vcc, s[90:91], s[0:1]
	v_readlane_b32 s5, v254, 18
	v_fmac_f32_e32 v5, 0x3e38aa3b, v67
	v_cndmask_b32_e32 v4, v4, v194, vcc
	s_and_b64 vcc, s[90:91], s[4:5]
	v_cndmask_b32_e32 v5, v5, v194, vcc
	v_cndmask_b32_e64 v11, v194, v3, s[68:69]
	v_cndmask_b32_e64 v14, v194, v4, s[68:69]
	v_cndmask_b32_e64 v12, v194, v5, s[68:69]
	v_max_f32_e32 v3, v11, v10
	v_max_f32_e32 v4, v14, v12
	v_readlane_b32 s4, v254, 19
	v_max3_f32 v2, v2, v3, v4
	v_fmamk_f32 v3, v149, 0x41000000, v1
	v_readlane_b32 s5, v254, 20
	v_fmac_f32_e32 v3, 0x3e38aa3b, v52
	v_fmamk_f32 v4, v149, 0x42200000, v1
	s_and_b64 vcc, s[90:91], s[4:5]
	v_fmac_f32_e32 v4, 0x3e38aa3b, v68
	v_cndmask_b32_e32 v3, v3, v194, vcc
	s_and_b64 vcc, s[90:91], s[20:21]
	v_cndmask_b32_e32 v4, v4, v194, vcc
	v_cndmask_b32_e64 v15, v194, v4, s[68:69]
	v_fmamk_f32 v4, v149, 0x41100000, v1
	v_fmac_f32_e32 v4, 0x3e38aa3b, v53
	v_fmamk_f32 v5, v149, 0x42240000, v1
	s_and_b64 vcc, s[90:91], s[22:23]
	v_fmac_f32_e32 v5, 0x3e38aa3b, v69
	v_cndmask_b32_e32 v4, v4, v194, vcc
	s_and_b64 vcc, s[90:91], s[24:25]
	v_cndmask_b32_e32 v5, v5, v194, vcc
	v_cndmask_b32_e64 v48, v194, v3, s[68:69]
	v_cndmask_b32_e64 v52, v194, v4, s[68:69]
	v_cndmask_b32_e64 v51, v194, v5, s[68:69]
	v_max_f32_e32 v3, v48, v15
	v_max_f32_e32 v4, v52, v51
	v_max3_f32 v2, v2, v3, v4
	v_fmamk_f32 v3, v149, 0x41200000, v1
	v_fmac_f32_e32 v3, 0x3e38aa3b, v54
	v_fmamk_f32 v4, v149, 0x42280000, v1
	s_and_b64 vcc, s[90:91], s[26:27]
	v_fmac_f32_e32 v4, 0x3e38aa3b, v70
	v_cndmask_b32_e32 v3, v3, v194, vcc
	s_and_b64 vcc, s[90:91], s[28:29]
	v_cndmask_b32_e32 v4, v4, v194, vcc
	v_cndmask_b32_e64 v53, v194, v4, s[68:69]
	v_fmamk_f32 v4, v149, 0x41300000, v1
	v_fmac_f32_e32 v4, 0x3e38aa3b, v55
	v_fmamk_f32 v5, v149, 0x422c0000, v1
	s_and_b64 vcc, s[90:91], s[30:31]
	v_fmac_f32_e32 v5, 0x3e38aa3b, v71
	v_cndmask_b32_e32 v4, v4, v194, vcc
	s_and_b64 vcc, s[90:91], s[34:35]
	v_cndmask_b32_e32 v5, v5, v194, vcc
	v_cndmask_b32_e64 v54, v194, v3, s[68:69]
	v_cndmask_b32_e64 v65, v194, v4, s[68:69]
	v_cndmask_b32_e64 v64, v194, v5, s[68:69]
	v_max_f32_e32 v3, v54, v53
	v_max_f32_e32 v4, v65, v64
	v_max3_f32 v2, v2, v3, v4
	v_fmamk_f32 v3, v149, 0x41800000, v1
	v_fmac_f32_e32 v3, 0x3e38aa3b, v56
	v_fmamk_f32 v4, v149, 0x42400000, v1
	s_and_b64 vcc, s[90:91], s[36:37]
	v_fmac_f32_e32 v4, 0x3e38aa3b, v72
	v_cndmask_b32_e32 v3, v3, v194, vcc
	s_and_b64 vcc, s[90:91], s[38:39]
	v_cndmask_b32_e32 v4, v4, v194, vcc
	v_cndmask_b32_e64 v66, v194, v4, s[68:69]
	v_fmamk_f32 v4, v149, 0x41880000, v1
	v_fmac_f32_e32 v4, 0x3e38aa3b, v57
	v_fmamk_f32 v5, v149, 0x42440000, v1
	s_and_b64 vcc, s[90:91], s[40:41]
	v_fmac_f32_e32 v5, 0x3e38aa3b, v73
	v_cndmask_b32_e32 v4, v4, v194, vcc
	s_and_b64 vcc, s[90:91], s[42:43]
	v_cndmask_b32_e32 v5, v5, v194, vcc
	v_cndmask_b32_e64 v67, v194, v3, s[68:69]
	v_cndmask_b32_e64 v68, v194, v4, s[68:69]
	v_cndmask_b32_e64 v57, v194, v5, s[68:69]
	v_max_f32_e32 v3, v67, v66
	v_max_f32_e32 v4, v68, v57
	v_max3_f32 v2, v2, v3, v4
	v_fmamk_f32 v3, v149, 0x41900000, v1
	v_fmac_f32_e32 v3, 0x3e38aa3b, v58
	v_fmamk_f32 v4, v149, 0x42480000, v1
	s_and_b64 vcc, s[90:91], s[44:45]
	v_fmac_f32_e32 v4, 0x3e38aa3b, v74
	v_cndmask_b32_e32 v3, v3, v194, vcc
	s_and_b64 vcc, s[90:91], s[46:47]
	v_cndmask_b32_e32 v4, v4, v194, vcc
	v_cndmask_b32_e64 v58, v194, v4, s[68:69]
	v_fmamk_f32 v4, v149, 0x41980000, v1
	v_fmac_f32_e32 v4, 0x3e38aa3b, v59
	v_fmamk_f32 v5, v149, 0x424c0000, v1
	s_and_b64 vcc, s[90:91], s[48:49]
	v_fmac_f32_e32 v5, 0x3e38aa3b, v75
	v_cndmask_b32_e32 v4, v4, v194, vcc
	s_and_b64 vcc, s[90:91], s[50:51]
	v_cndmask_b32_e32 v5, v5, v194, vcc
	v_cndmask_b32_e64 v69, v194, v3, s[68:69]
	v_cndmask_b32_e64 v59, v194, v4, s[68:69]
	v_cndmask_b32_e64 v49, v194, v5, s[68:69]
	v_max_f32_e32 v3, v69, v58
	v_max_f32_e32 v4, v59, v49
	v_max3_f32 v2, v2, v3, v4
	v_fmamk_f32 v3, v149, 0x41c00000, v1
	v_fmac_f32_e32 v3, 0x3e38aa3b, v60
	s_and_b64 vcc, s[90:91], s[52:53]
	v_fmamk_f32 v4, v149, 0x42600000, v1
	v_cndmask_b32_e32 v3, v3, v194, vcc
	v_fmac_f32_e32 v4, 0x3e38aa3b, v76
	s_and_b64 vcc, s[90:91], s[54:55]
	v_cndmask_b32_e64 v13, v194, v3, s[68:69]
	v_fmamk_f32 v3, v149, 0x41c80000, v1
	v_cndmask_b32_e32 v4, v4, v194, vcc
	v_fmac_f32_e32 v3, 0x3e38aa3b, v61
	v_fmamk_f32 v50, v149, 0x42640000, v1
	s_and_b64 vcc, s[90:91], s[56:57]
	v_fmac_f32_e32 v50, 0x3e38aa3b, v77
	v_cndmask_b32_e32 v3, v3, v194, vcc
	s_and_b64 vcc, s[90:91], s[58:59]
	v_cndmask_b32_e32 v55, v50, v194, vcc
	v_cndmask_b32_e64 v4, v194, v4, s[68:69]
	v_cndmask_b32_e64 v50, v194, v3, s[68:69]
	v_cndmask_b32_e64 v3, v194, v55, s[68:69]
	v_max_f32_e32 v5, v13, v4
	v_max_f32_e32 v55, v50, v3
	v_max3_f32 v2, v2, v5, v55
	v_fmamk_f32 v5, v149, 0x41d00000, v1
	v_fmac_f32_e32 v5, 0x3e38aa3b, v62
	v_fmamk_f32 v55, v149, 0x42680000, v1
	s_and_b64 vcc, s[90:91], s[60:61]
	v_fmac_f32_e32 v55, 0x3e38aa3b, v78
	v_cndmask_b32_e32 v5, v5, v194, vcc
	s_and_b64 vcc, s[90:91], s[62:63]
	v_cndmask_b32_e32 v56, v55, v194, vcc
	v_cndmask_b32_e64 v55, v194, v5, s[68:69]
	v_cndmask_b32_e64 v5, v194, v56, s[68:69]
	v_fmamk_f32 v56, v149, 0x41d80000, v1
	v_fmac_f32_e32 v56, 0x3e38aa3b, v63
	v_fmac_f32_e32 v1, 0x426c0000, v149
	s_and_b64 vcc, s[90:91], s[64:65]
	v_fmac_f32_e32 v1, 0x3e38aa3b, v79
	v_cndmask_b32_e32 v56, v56, v194, vcc
	s_and_b64 vcc, s[90:91], s[66:67]
	v_cndmask_b32_e32 v1, v1, v194, vcc
	v_cndmask_b32_e64 v56, v194, v56, s[68:69]
	v_cndmask_b32_e64 v1, v194, v1, s[68:69]
	v_max_f32_e32 v60, v55, v5
	v_max_f32_e32 v61, v56, v1
	v_max3_f32 v2, v2, v60, v61
	v_mov_b32_e32 v60, v2
	s_nop 1
	v_permlane32_swap_b32_e32 v2, v60
	v_max3_f32 v161, v160, v2, v60
	v_sub_f32_e32 v2, v160, v161
	v_exp_f32_e32 v2, v2
	s_nop 0
	v_cmp_neq_f32_e32 vcc, 1.0, v2
	s_cbranch_vccz .LBB0_848
	v_pk_mul_f32 v[46:47], v[46:47], v[2:3] op_sel_hi:[1,0]
	v_pk_mul_f32 v[44:45], v[44:45], v[2:3] op_sel_hi:[1,0]
	v_pk_mul_f32 v[42:43], v[42:43], v[2:3] op_sel_hi:[1,0]
	v_pk_mul_f32 v[40:41], v[40:41], v[2:3] op_sel_hi:[1,0]
	v_pk_mul_f32 v[38:39], v[38:39], v[2:3] op_sel_hi:[1,0]
	v_pk_mul_f32 v[36:37], v[36:37], v[2:3] op_sel_hi:[1,0]
	v_pk_mul_f32 v[34:35], v[34:35], v[2:3] op_sel_hi:[1,0]
	v_pk_mul_f32 v[32:33], v[32:33], v[2:3] op_sel_hi:[1,0]
	v_pk_mul_f32 v[30:31], v[30:31], v[2:3] op_sel_hi:[1,0]
	v_pk_mul_f32 v[28:29], v[28:29], v[2:3] op_sel_hi:[1,0]
	v_pk_mul_f32 v[26:27], v[26:27], v[2:3] op_sel_hi:[1,0]
	v_pk_mul_f32 v[24:25], v[24:25], v[2:3] op_sel_hi:[1,0]
	v_pk_mul_f32 v[22:23], v[22:23], v[2:3] op_sel_hi:[1,0]
	v_pk_mul_f32 v[20:21], v[20:21], v[2:3] op_sel_hi:[1,0]
	v_pk_mul_f32 v[18:19], v[18:19], v[2:3] op_sel_hi:[1,0]
	v_pk_mul_f32 v[16:17], v[16:17], v[2:3] op_sel_hi:[1,0]
